# stack6 + up K-loop: leading wave group waits for its LDS-DMA after the MFMA block, trailing group issues each staging group one ping-pong interval earlier (inside the preceding MFMA phase)
# baseline (speedup 1.0000x reference)
; #define PG8_STAGE(bufoff, gbase, voff) do { _Pragma("unroll") for (int _i = 0; _i < 2; ++_i) \
;         __builtin_amdgcn_global_load_lds((const unsigned*)((const char*)(gbase) + (voff)[_i]), (PG8_LAS unsigned*)(lds + (bufoff) + ldsw + _i * 8192), 16, 0, 0); } while (0)
; #define PG8_WAIT_V(n) asm volatile("s_waitcnt vmcnt(" #n ")" ::: "memory")
; #define PG8_BAR __builtin_amdgcn_s_barrier()
; template <class Epi, class Sched, bool ALIGN_EPI = false, bool SP2 = false>
; __device__ __forceinline__ void gemm_phase(PG8_LAS unsigned char* lds, const Gemm g, const Sched& S, const Epi& E, int wid_in) {
;     ...
;     for (int i = 0; i < 2; ++i) { int R, C; stage_rc(tid * 16 + i * 8192, R, C); const int Rb = Epi::PERM ? ((R & ~31) + perm32(R & 31)) : R;
;         voffA[i] = (unsigned)(R * K + C) * 2u; voffB[i] = (unsigned)(Rb * K + C) * 2u; }
;     const size_t kstep = (size_t)(BK * 2);
;     const size_t hstep = (size_t)HALF * K * 2;
;     const size_t tstep = 2 * hstep;
;     const unsigned ldsw = (unsigned)wid * 1024u;
;     const int aoff = lds_byte(wr * 64 + fr, fq * 8), boff = lds_byte(wc * 32 + fr, fq * 8);
;     ...
;         PG8_STAGE(PG8_SB(1, 0), cB + kstep, voffB); PG8_STAGE(PG8_SA(1, 0), cA + kstep, voffA); PG8_STAGE(PG8_SB(1, 1), cB + hstep + kstep, voffB);
;         PG8_WAIT_V(6); PG8_BAR;
;     } else {
;         PG8_STAGE(PG8_SB(0, 0), cB, voffB); PG8_STAGE(PG8_SA(0, 0), cA, voffA); PG8_STAGE(PG8_SB(0, 1), cB + hstep, voffB); PG8_STAGE(PG8_SA(0, 1), cA + hstep, voffA);
;         if (wr == 1) PG8_BAR;
;         PG8_WAIT_V(4); PG8_BAR;
;         PG8_STAGE(PG8_SB(1, 0), cB + kstep, voffB); PG8_STAGE(PG8_SA(1, 0), cA + kstep, voffA); PG8_STAGE(PG8_SB(1, 1), cB + hstep + kstep, voffB);
;         PG8_WAIT_V(6); PG8_BAR;
.LBB0_1147:
	s_add_u32 s12, s8, 0x23000000
	v_and_b32_e32 v18, 48, v16
	v_lshlrev_b32_e32 v20, 6, v16
	s_movk_i32 s8, 0x3c0
	s_addc_u32 s13, s9, 0
	v_and_or_b32 v18, v20, s8, v18
	s_lshl_b32 s8, s47, 5
	s_and_b32 s39, s8, 0x60
	s_add_i32 m0, s34, 0x18000
	v_lshl_add_u64 v[8:9], v[8:9], 0, s[94:95]
	s_lshl_b32 s38, s14, 6
	v_ashrrev_i32_e32 v17, 6, v16
	s_lshr_b32 s8, s39, 3
	s_waitcnt vmcnt(2)
	s_barrier
	global_load_lds_dwordx4 v[8:9], off
	v_lshl_add_u64 v[6:7], v[6:7], 0, s[94:95]
	s_add_i32 m0, s34, 0x1a000
	s_add_i32 s48, s34, 0x8000
	s_add_i32 s52, s34, 0xa000
	v_lshlrev_b32_e32 v19, 10, v17
	v_add_lshl_u32 v17, s8, v17, 10
	global_load_lds_dwordx4 v[6:7], off
	v_lshl_add_u64 v[2:3], v[2:3], 0, s[94:95]
	s_mov_b32 m0, s48
	s_add_u32 s8, s26, 0x80080
	global_load_lds_dwordx4 v[2:3], off
	v_lshl_add_u64 v[2:3], v[4:5], 0, s[94:95]
	s_mov_b32 m0, s52
	s_addc_u32 s9, s27, 0
	global_load_lds_dwordx4 v[2:3], off
	s_add_i32 m0, s34, 0x1c000
	v_lshl_add_u64 v[2:3], s[8:9], 0, v[0:1]
	global_load_lds_dwordx4 v[2:3], off
	v_lshl_add_u64 v[2:3], s[8:9], 0, v[130:131]
	s_add_i32 m0, s34, 0x1e000
	v_lshlrev_b32_e32 v16, 2, v16
	global_load_lds_dwordx4 v[2:3], off
	v_lshlrev_b32_e32 v2, 15, v10
	v_and_b32_e32 v2, 0xffff0000, v2
	v_lshl_add_u32 v2, v11, 12, v2
	v_and_b32_e32 v3, 1, v10
	v_lshl_or_b32 v2, v3, 6, v2
	v_lshl_add_u32 v136, v12, 1, v2
	v_lshlrev_b32_e32 v2, 15, v13
	v_and_b32_e32 v2, 0xffff0000, v2
	v_lshl_add_u32 v19, s14, 13, v19
	v_and_b32_e32 v16, 32, v16
	s_waitcnt vmcnt(6)
	v_lshl_add_u32 v2, v14, 12, v2
	v_and_b32_e32 v3, 1, v13
	v_bitop3_b32 v19, v18, v19, v16 bitop3:0xde
	s_cmp_lt_u32 s47, 4
	v_lshl_or_b32 v2, v3, 6, v2
	v_readlane_b32 s8, v255, 19
	v_bitop3_b32 v142, v17, v18, v16 bitop3:0xf6
	s_cselect_b64 s[14:15], -1, 0
	v_mov_b32_e32 v137, v1
	v_lshl_add_u32 v138, v15, 1, v2
	v_mov_b32_e32 v139, v1
	s_mov_b32 s53, 0
	v_add_u32_e32 v143, 0, v19
	v_readlane_b32 s62, v255, 16
	s_mov_b32 s61, s8
	s_barrier
	v_readlane_b32 s9, v255, 20
	s_cmp_lt_u32 s47, 4
	s_cbranch_scc1 .Lup2_pre_skip
	s_add_u32 s98, s24, 0x80080
	s_addc_u32 s99, s25, 0
	s_add_i32 m0, s34, 0xc000
	s_nop 0
	global_load_lds_dwordx4 v138, s[98:99]
	s_add_i32 m0, s34, 0xe000
	s_nop 0
	global_load_lds_dwordx4 v136, s[98:99]
.Lup2_pre_skip:
	s_branch .LBB0_1150
.LBB0_1148:
	s_mov_b64 s[8:9], 0

; #define PG8_STAGE(bufoff, gbase, voff) do { _Pragma("unroll") for (int _i = 0; _i < 2; ++_i) \
;         __builtin_amdgcn_global_load_lds((const unsigned*)((const char*)(gbase) + (voff)[_i]), (PG8_LAS unsigned*)(lds + (bufoff) + ldsw + _i * 8192), 16, 0, 0); } while (0)
; #define PG8_LDA(dst, b, h) do { _Pragma("unroll") for (int m = 0; m < 4; ++m) _Pragma("unroll") for (int k = 0; k < 2; ++k) dst[m][k] = *(const PG8_LAS bf16x8*)(lds + PG8_SA(b, h) + aoff + m * 2048 + k * 1024); } while (0)
; #define PG8_LDB(dst, b, h) do { _Pragma("unroll") for (int n = 0; n < 2; ++n) _Pragma("unroll") for (int k = 0; k < 2; ++k) dst[n][k] = *(const PG8_LAS bf16x8*)(lds + PG8_SB(b, h) + boff + n * 2048 + k * 1024); } while (0)
; #define PG8_MMA(ai, bj, At, Bt) do { __builtin_amdgcn_s_setprio(1); _Pragma("unroll") for (int m = 0; m < 4; ++m) _Pragma("unroll") for (int n = 0; n < 2; ++n) _Pragma("unroll") for (int k = 0; k < 2; ++k) \
;         acc[ai][bj][m][n] = __builtin_amdgcn_mfma_f32_16x16x32_bf16(Bt[n][k], At[m][k], acc[ai][bj][m][n], 0, 0, 0); __builtin_amdgcn_s_setprio(0); } while (0)
; #define PG8_WAIT_V(n) asm volatile("s_waitcnt vmcnt(" #n ")" ::: "memory")
; #define PG8_BAR __builtin_amdgcn_s_barrier()
; template <class Epi, class Sched, bool ALIGN_EPI = false, bool SP2 = false>
; __device__ __forceinline__ void gemm_phase(PG8_LAS unsigned char* lds, const Gemm g, const Sched& S, const Epi& E, int wid_in) {
;     ...
;         for (int t = 0; t < nt; t += 2) {
;             const bool last = (t == nt - 2);
;             const char* a1 = cA + (size_t)(t + 1) * kstep;
;             const char* a2 = last ? nA : cA + (size_t)(t + 2) * kstep; const char* b2 = last ? nB : cB + (size_t)(t + 2) * kstep;
;             const char* a3 = a2 + kstep; const char* b3 = b2 + kstep;
;             if (last && has_next) S.a_ready(nxt);
;             if constexpr (SP2) {
;             PG8_LDB(B0, 0, 0); PG8_LDB(B1, 0, 1); PG8_SCHED; PG8_LDA(At, 0, 0); PG8_STAGE(PG8_SA(1, 1), a1 + hstep, voffA);
;             PG8_WAIT_V(8); PG8_WAIT_L(0); PG8_BAR; PG8_MMA(0, 0, At, B0); PG8_MMA(0, 1, At, B1); PG8_BAR; PG8_SCHED;
;             PG8_LDA(At, 0, 1); PG8_STAGE(PG8_SB(0, 0), b2, voffB); PG8_STAGE(PG8_SB(0, 1), b2 + hstep, voffB); PG8_STAGE(PG8_SA(0, 0), a2, voffA);
;             PG8_WAIT_V(8); PG8_WAIT_L(0); PG8_BAR; PG8_MMA(1, 0, At, B0); PG8_MMA(1, 1, At, B1); PG8_BAR; PG8_SCHED;
.Lprio_skip_4:
.LBB0_1153:
	s_add_u32 s26, s24, 0xfff80080
	s_addc_u32 s27, s25, -1
	s_cmp_eq_u32 s73, 28
	s_cselect_b32 s29, s19, s27
	s_cselect_b32 s28, s64, s26
	s_cselect_b32 s27, s17, s63
	s_cselect_b32 s26, s65, s72
	s_add_u32 s40, s26, 0x80000
	s_addc_u32 s41, s27, 0
	s_add_u32 s98, s26, 0x80
	s_addc_u32 s99, s27, 0
	s_add_u32 s100, s28, 0x80
	s_addc_u32 s101, s29, 0
	v_add_u32_e32 v224, 0x10000, v142
	s_cmp_lt_u32 s47, 4
	s_cbranch_scc0 .Lup2_B
	ds_read_b128 v[144:147], v224 offset:0
	ds_read_b128 v[148:151], v224 offset:1024
	ds_read_b128 v[152:155], v224 offset:2048
	ds_read_b128 v[156:159], v224 offset:3072
	ds_read_b128 v[160:163], v224 offset:16384
	ds_read_b128 v[164:167], v224 offset:17408
	ds_read_b128 v[168:171], v224 offset:18432
	ds_read_b128 v[172:175], v224 offset:19456
	ds_read_b128 v[176:179], v143 offset:0
	ds_read_b128 v[180:183], v143 offset:1024
	ds_read_b128 v[184:187], v143 offset:2048
	ds_read_b128 v[188:191], v143 offset:3072
	ds_read_b128 v[208:211], v143 offset:4096
	ds_read_b128 v[212:215], v143 offset:5120
	ds_read_b128 v[216:219], v143 offset:6144
	ds_read_b128 v[220:223], v143 offset:7168
	s_add_i32 m0, s34, 0xc000
	s_nop 0
	global_load_lds_dwordx4 v138, s[24:25]
	s_add_i32 m0, s34, 0xe000
	s_nop 0
	global_load_lds_dwordx4 v136, s[24:25]
	s_waitcnt lgkmcnt(0)
	s_barrier
	v_mfma_f32_16x16x32_bf16 v[126:129], v[144:147], v[176:179], v[126:129]
	v_mfma_f32_16x16x32_bf16 v[122:125], v[152:155], v[176:179], v[122:125]
	v_mfma_f32_16x16x32_bf16 v[110:113], v[144:147], v[184:187], v[110:113]
	v_mfma_f32_16x16x32_bf16 v[106:109], v[152:155], v[184:187], v[106:109]
	v_mfma_f32_16x16x32_bf16 v[94:97], v[144:147], v[208:211], v[94:97]
	v_mfma_f32_16x16x32_bf16 v[90:93], v[152:155], v[208:211], v[90:93]
	v_mfma_f32_16x16x32_bf16 v[78:81], v[144:147], v[216:219], v[78:81]
	v_mfma_f32_16x16x32_bf16 v[74:77], v[152:155], v[216:219], v[74:77]
	v_mfma_f32_16x16x32_bf16 v[126:129], v[148:151], v[180:183], v[126:129]
	v_mfma_f32_16x16x32_bf16 v[122:125], v[156:159], v[180:183], v[122:125]
	v_mfma_f32_16x16x32_bf16 v[110:113], v[148:151], v[188:191], v[110:113]
	v_mfma_f32_16x16x32_bf16 v[106:109], v[156:159], v[188:191], v[106:109]
	v_mfma_f32_16x16x32_bf16 v[94:97], v[148:151], v[212:215], v[94:97]
	v_mfma_f32_16x16x32_bf16 v[90:93], v[156:159], v[212:215], v[90:93]
	v_mfma_f32_16x16x32_bf16 v[78:81], v[148:151], v[220:223], v[78:81]
	v_mfma_f32_16x16x32_bf16 v[74:77], v[156:159], v[220:223], v[74:77]
	v_mfma_f32_16x16x32_bf16 v[118:121], v[160:163], v[176:179], v[118:121]
	v_mfma_f32_16x16x32_bf16 v[114:117], v[168:171], v[176:179], v[114:117]
	v_mfma_f32_16x16x32_bf16 v[102:105], v[160:163], v[184:187], v[102:105]
	v_mfma_f32_16x16x32_bf16 v[98:101], v[168:171], v[184:187], v[98:101]
	v_mfma_f32_16x16x32_bf16 v[86:89], v[160:163], v[208:211], v[86:89]
	v_mfma_f32_16x16x32_bf16 v[82:85], v[168:171], v[208:211], v[82:85]
	v_mfma_f32_16x16x32_bf16 v[70:73], v[160:163], v[216:219], v[70:73]
	v_mfma_f32_16x16x32_bf16 v[66:69], v[168:171], v[216:219], v[66:69]
	v_mfma_f32_16x16x32_bf16 v[118:121], v[164:167], v[180:183], v[118:121]
	v_mfma_f32_16x16x32_bf16 v[114:117], v[172:175], v[180:183], v[114:117]
	v_mfma_f32_16x16x32_bf16 v[102:105], v[164:167], v[188:191], v[102:105]
	v_mfma_f32_16x16x32_bf16 v[98:101], v[172:175], v[188:191], v[98:101]
	v_mfma_f32_16x16x32_bf16 v[86:89], v[164:167], v[212:215], v[86:89]
	v_mfma_f32_16x16x32_bf16 v[82:85], v[172:175], v[212:215], v[82:85]
	v_mfma_f32_16x16x32_bf16 v[70:73], v[164:167], v[220:223], v[70:73]
	v_mfma_f32_16x16x32_bf16 v[66:69], v[172:175], v[220:223], v[66:69]
	s_waitcnt vmcnt(8)
	s_barrier
	ds_read_b128 v[176:179], v143 offset:16384
	ds_read_b128 v[180:183], v143 offset:17408
	ds_read_b128 v[184:187], v143 offset:18432
	ds_read_b128 v[188:191], v143 offset:19456
	ds_read_b128 v[208:211], v143 offset:20480
	ds_read_b128 v[212:215], v143 offset:21504
	ds_read_b128 v[216:219], v143 offset:22528
	ds_read_b128 v[220:223], v143 offset:23552
	s_add_i32 m0, s59, 0x10000
	s_nop 0
	global_load_lds_dwordx4 v0, s[26:27]
	s_add_i32 m0, s59, 0x12000
	s_nop 0
	global_load_lds_dwordx4 v130, s[26:27]
	s_add_i32 m0, s59, 0x14000
	s_nop 0
	global_load_lds_dwordx4 v0, s[40:41]
	s_add_i32 m0, s59, 0x16000
	s_nop 0
	global_load_lds_dwordx4 v130, s[40:41]
	s_mov_b32 m0, s34
	s_nop 0
	global_load_lds_dwordx4 v134, s[28:29]
	s_mov_b32 m0, s35
	s_nop 0
	global_load_lds_dwordx4 v132, s[28:29]
	s_waitcnt lgkmcnt(0)
	s_barrier
	v_mfma_f32_16x16x32_bf16 v[62:65], v[144:147], v[176:179], v[62:65]
	v_mfma_f32_16x16x32_bf16 v[58:61], v[152:155], v[176:179], v[58:61]
	v_mfma_f32_16x16x32_bf16 v[46:49], v[144:147], v[184:187], v[46:49]
	v_mfma_f32_16x16x32_bf16 v[42:45], v[152:155], v[184:187], v[42:45]
	v_mfma_f32_16x16x32_bf16 v[30:33], v[144:147], v[208:211], v[30:33]
	v_mfma_f32_16x16x32_bf16 v[26:29], v[152:155], v[208:211], v[26:29]
	v_mfma_f32_16x16x32_bf16 v[14:17], v[144:147], v[216:219], v[14:17]
	v_mfma_f32_16x16x32_bf16 v[10:13], v[152:155], v[216:219], v[10:13]
	v_mfma_f32_16x16x32_bf16 v[62:65], v[148:151], v[180:183], v[62:65]
	v_mfma_f32_16x16x32_bf16 v[58:61], v[156:159], v[180:183], v[58:61]
	v_mfma_f32_16x16x32_bf16 v[46:49], v[148:151], v[188:191], v[46:49]
	v_mfma_f32_16x16x32_bf16 v[42:45], v[156:159], v[188:191], v[42:45]
	v_mfma_f32_16x16x32_bf16 v[30:33], v[148:151], v[212:215], v[30:33]
	v_mfma_f32_16x16x32_bf16 v[26:29], v[156:159], v[212:215], v[26:29]
	v_mfma_f32_16x16x32_bf16 v[14:17], v[148:151], v[220:223], v[14:17]
	v_mfma_f32_16x16x32_bf16 v[10:13], v[156:159], v[220:223], v[10:13]
	v_mfma_f32_16x16x32_bf16 v[54:57], v[160:163], v[176:179], v[54:57]
	v_mfma_f32_16x16x32_bf16 v[50:53], v[168:171], v[176:179], v[50:53]
	v_mfma_f32_16x16x32_bf16 v[38:41], v[160:163], v[184:187], v[38:41]
	v_mfma_f32_16x16x32_bf16 v[34:37], v[168:171], v[184:187], v[34:37]
	v_mfma_f32_16x16x32_bf16 v[22:25], v[160:163], v[208:211], v[22:25]
	v_mfma_f32_16x16x32_bf16 v[18:21], v[168:171], v[208:211], v[18:21]
	v_mfma_f32_16x16x32_bf16 v[6:9], v[160:163], v[216:219], v[6:9]
	v_mfma_f32_16x16x32_bf16 v[2:5], v[168:171], v[216:219], v[2:5]
	v_mfma_f32_16x16x32_bf16 v[54:57], v[164:167], v[180:183], v[54:57]
	v_mfma_f32_16x16x32_bf16 v[50:53], v[172:175], v[180:183], v[50:53]
	v_mfma_f32_16x16x32_bf16 v[38:41], v[164:167], v[188:191], v[38:41]
	v_mfma_f32_16x16x32_bf16 v[34:37], v[172:175], v[188:191], v[34:37]
	v_mfma_f32_16x16x32_bf16 v[22:25], v[164:167], v[212:215], v[22:25]
	v_mfma_f32_16x16x32_bf16 v[18:21], v[172:175], v[212:215], v[18:21]
	v_mfma_f32_16x16x32_bf16 v[6:9], v[164:167], v[220:223], v[6:9]
	v_mfma_f32_16x16x32_bf16 v[2:5], v[172:175], v[220:223], v[2:5]
	s_waitcnt vmcnt(8)
	s_barrier
; #define PG8_STAGE(bufoff, gbase, voff) do { _Pragma("unroll") for (int _i = 0; _i < 2; ++_i) \
;         __builtin_amdgcn_global_load_lds((const unsigned*)((const char*)(gbase) + (voff)[_i]), (PG8_LAS unsigned*)(lds + (bufoff) + ldsw + _i * 8192), 16, 0, 0); } while (0)
; #define PG8_LDA(dst, b, h) do { _Pragma("unroll") for (int m = 0; m < 4; ++m) _Pragma("unroll") for (int k = 0; k < 2; ++k) dst[m][k] = *(const PG8_LAS bf16x8*)(lds + PG8_SA(b, h) + aoff + m * 2048 + k * 1024); } while (0)
; #define PG8_LDB(dst, b, h) do { _Pragma("unroll") for (int n = 0; n < 2; ++n) _Pragma("unroll") for (int k = 0; k < 2; ++k) dst[n][k] = *(const PG8_LAS bf16x8*)(lds + PG8_SB(b, h) + boff + n * 2048 + k * 1024); } while (0)
; #define PG8_MMA(ai, bj, At, Bt) do { __builtin_amdgcn_s_setprio(1); _Pragma("unroll") for (int m = 0; m < 4; ++m) _Pragma("unroll") for (int n = 0; n < 2; ++n) _Pragma("unroll") for (int k = 0; k < 2; ++k) \
;         acc[ai][bj][m][n] = __builtin_amdgcn_mfma_f32_16x16x32_bf16(Bt[n][k], At[m][k], acc[ai][bj][m][n], 0, 0, 0); __builtin_amdgcn_s_setprio(0); } while (0)
; #define PG8_WAIT_V(n) asm volatile("s_waitcnt vmcnt(" #n ")" ::: "memory")
; #define PG8_WAIT_L(n) asm volatile("s_waitcnt lgkmcnt(" #n ")" ::: "memory")
; #define PG8_BAR __builtin_amdgcn_s_barrier()
; #define PG8_SCHED __builtin_amdgcn_sched_barrier(0)
; template <class Epi, class Sched, bool ALIGN_EPI = false, bool SP2 = false>
; __device__ __forceinline__ void gemm_phase(PG8_LAS unsigned char* lds, const Gemm g, const Sched& S, const Epi& E, int wid_in) {
;     ...
;             PG8_LDB(B0, 1, 0); PG8_LDB(B1, 1, 1); PG8_SCHED; PG8_LDA(At, 1, 0); PG8_STAGE(PG8_SA(0, 1), a2 + hstep, voffA);
;             PG8_WAIT_V(8); PG8_WAIT_L(0); PG8_BAR; PG8_MMA(0, 0, At, B0); PG8_MMA(0, 1, At, B1); PG8_BAR; PG8_SCHED;
;             PG8_LDA(At, 1, 1); PG8_STAGE(PG8_SB(1, 0), b3, voffB); PG8_STAGE(PG8_SB(1, 1), b3 + hstep, voffB); PG8_STAGE(PG8_SA(1, 0), a3, voffA);
;             PG8_WAIT_V(8); PG8_WAIT_L(0); PG8_BAR; PG8_MMA(1, 0, At, B0); PG8_MMA(1, 1, At, B1); PG8_BAR; PG8_SCHED;
	ds_read_b128 v[144:147], v224 offset:32768
	ds_read_b128 v[148:151], v224 offset:33792
	ds_read_b128 v[152:155], v224 offset:34816
	ds_read_b128 v[156:159], v224 offset:35840
	ds_read_b128 v[160:163], v224 offset:49152
	ds_read_b128 v[164:167], v224 offset:50176
	ds_read_b128 v[168:171], v224 offset:51200
	ds_read_b128 v[172:175], v224 offset:52224
	ds_read_b128 v[176:179], v143 offset:32768
	ds_read_b128 v[180:183], v143 offset:33792
	ds_read_b128 v[184:187], v143 offset:34816
	ds_read_b128 v[188:191], v143 offset:35840
	ds_read_b128 v[208:211], v143 offset:36864
	ds_read_b128 v[212:215], v143 offset:37888
	ds_read_b128 v[216:219], v143 offset:38912
	ds_read_b128 v[220:223], v143 offset:39936
	s_add_u32 s28, s28, 0x80000
	s_addc_u32 s29, s29, 0
	s_mov_b32 m0, s36
	s_nop 0
	global_load_lds_dwordx4 v134, s[28:29]
	s_mov_b32 m0, s37
	s_nop 0
	global_load_lds_dwordx4 v132, s[28:29]
	s_waitcnt lgkmcnt(0)
	s_barrier
	v_mfma_f32_16x16x32_bf16 v[126:129], v[144:147], v[176:179], v[126:129]
	v_mfma_f32_16x16x32_bf16 v[122:125], v[152:155], v[176:179], v[122:125]
	v_mfma_f32_16x16x32_bf16 v[110:113], v[144:147], v[184:187], v[110:113]
	v_mfma_f32_16x16x32_bf16 v[106:109], v[152:155], v[184:187], v[106:109]
	v_mfma_f32_16x16x32_bf16 v[94:97], v[144:147], v[208:211], v[94:97]
	v_mfma_f32_16x16x32_bf16 v[90:93], v[152:155], v[208:211], v[90:93]
	v_mfma_f32_16x16x32_bf16 v[78:81], v[144:147], v[216:219], v[78:81]
	v_mfma_f32_16x16x32_bf16 v[74:77], v[152:155], v[216:219], v[74:77]
	v_mfma_f32_16x16x32_bf16 v[126:129], v[148:151], v[180:183], v[126:129]
	v_mfma_f32_16x16x32_bf16 v[122:125], v[156:159], v[180:183], v[122:125]
	v_mfma_f32_16x16x32_bf16 v[110:113], v[148:151], v[188:191], v[110:113]
	v_mfma_f32_16x16x32_bf16 v[106:109], v[156:159], v[188:191], v[106:109]
	v_mfma_f32_16x16x32_bf16 v[94:97], v[148:151], v[212:215], v[94:97]
	v_mfma_f32_16x16x32_bf16 v[90:93], v[156:159], v[212:215], v[90:93]
	v_mfma_f32_16x16x32_bf16 v[78:81], v[148:151], v[220:223], v[78:81]
	v_mfma_f32_16x16x32_bf16 v[74:77], v[156:159], v[220:223], v[74:77]
	v_mfma_f32_16x16x32_bf16 v[118:121], v[160:163], v[176:179], v[118:121]
	v_mfma_f32_16x16x32_bf16 v[114:117], v[168:171], v[176:179], v[114:117]
	v_mfma_f32_16x16x32_bf16 v[102:105], v[160:163], v[184:187], v[102:105]
	v_mfma_f32_16x16x32_bf16 v[98:101], v[168:171], v[184:187], v[98:101]
	v_mfma_f32_16x16x32_bf16 v[86:89], v[160:163], v[208:211], v[86:89]
	v_mfma_f32_16x16x32_bf16 v[82:85], v[168:171], v[208:211], v[82:85]
	v_mfma_f32_16x16x32_bf16 v[70:73], v[160:163], v[216:219], v[70:73]
	v_mfma_f32_16x16x32_bf16 v[66:69], v[168:171], v[216:219], v[66:69]
	v_mfma_f32_16x16x32_bf16 v[118:121], v[164:167], v[180:183], v[118:121]
	v_mfma_f32_16x16x32_bf16 v[114:117], v[172:175], v[180:183], v[114:117]
	v_mfma_f32_16x16x32_bf16 v[102:105], v[164:167], v[188:191], v[102:105]
	v_mfma_f32_16x16x32_bf16 v[98:101], v[172:175], v[188:191], v[98:101]
	v_mfma_f32_16x16x32_bf16 v[86:89], v[164:167], v[212:215], v[86:89]
	v_mfma_f32_16x16x32_bf16 v[82:85], v[172:175], v[212:215], v[82:85]
	v_mfma_f32_16x16x32_bf16 v[70:73], v[164:167], v[220:223], v[70:73]
	v_mfma_f32_16x16x32_bf16 v[66:69], v[172:175], v[220:223], v[66:69]
	s_waitcnt vmcnt(8)
	s_barrier
	ds_read_b128 v[176:179], v143 offset:49152
	ds_read_b128 v[180:183], v143 offset:50176
	ds_read_b128 v[184:187], v143 offset:51200
	ds_read_b128 v[188:191], v143 offset:52224
	ds_read_b128 v[208:211], v143 offset:53248
	ds_read_b128 v[212:215], v143 offset:54272
	ds_read_b128 v[216:219], v143 offset:55296
	ds_read_b128 v[220:223], v143 offset:56320
	s_add_i32 m0, s59, 0x18000
	s_nop 0
	global_load_lds_dwordx4 v0, s[98:99]
	s_add_i32 m0, s59, 0x1a000
	s_nop 0
	global_load_lds_dwordx4 v130, s[98:99]
	s_add_u32 s26, s26, 0x80080
	s_addc_u32 s27, s27, 0
	s_add_i32 m0, s59, 0x1c000
	s_nop 0
	global_load_lds_dwordx4 v0, s[26:27]
	s_add_i32 m0, s59, 0x1e000
	s_nop 0
	global_load_lds_dwordx4 v130, s[26:27]
	s_mov_b32 m0, s48
	s_nop 0
	global_load_lds_dwordx4 v134, s[100:101]
	s_mov_b32 m0, s52
	s_nop 0
	global_load_lds_dwordx4 v132, s[100:101]
	s_waitcnt lgkmcnt(0)
	s_barrier
	v_mfma_f32_16x16x32_bf16 v[62:65], v[144:147], v[176:179], v[62:65]
	v_mfma_f32_16x16x32_bf16 v[58:61], v[152:155], v[176:179], v[58:61]
	v_mfma_f32_16x16x32_bf16 v[46:49], v[144:147], v[184:187], v[46:49]
	v_mfma_f32_16x16x32_bf16 v[42:45], v[152:155], v[184:187], v[42:45]
	v_mfma_f32_16x16x32_bf16 v[30:33], v[144:147], v[208:211], v[30:33]
	v_mfma_f32_16x16x32_bf16 v[26:29], v[152:155], v[208:211], v[26:29]
	v_mfma_f32_16x16x32_bf16 v[14:17], v[144:147], v[216:219], v[14:17]
	v_mfma_f32_16x16x32_bf16 v[10:13], v[152:155], v[216:219], v[10:13]
	v_mfma_f32_16x16x32_bf16 v[62:65], v[148:151], v[180:183], v[62:65]
	v_mfma_f32_16x16x32_bf16 v[58:61], v[156:159], v[180:183], v[58:61]
	v_mfma_f32_16x16x32_bf16 v[46:49], v[148:151], v[188:191], v[46:49]
	v_mfma_f32_16x16x32_bf16 v[42:45], v[156:159], v[188:191], v[42:45]
	v_mfma_f32_16x16x32_bf16 v[30:33], v[148:151], v[212:215], v[30:33]
	v_mfma_f32_16x16x32_bf16 v[26:29], v[156:159], v[212:215], v[26:29]
	v_mfma_f32_16x16x32_bf16 v[14:17], v[148:151], v[220:223], v[14:17]
	v_mfma_f32_16x16x32_bf16 v[10:13], v[156:159], v[220:223], v[10:13]
	v_mfma_f32_16x16x32_bf16 v[54:57], v[160:163], v[176:179], v[54:57]
	v_mfma_f32_16x16x32_bf16 v[50:53], v[168:171], v[176:179], v[50:53]
	v_mfma_f32_16x16x32_bf16 v[38:41], v[160:163], v[184:187], v[38:41]
	v_mfma_f32_16x16x32_bf16 v[34:37], v[168:171], v[184:187], v[34:37]
	v_mfma_f32_16x16x32_bf16 v[22:25], v[160:163], v[208:211], v[22:25]
	v_mfma_f32_16x16x32_bf16 v[18:21], v[168:171], v[208:211], v[18:21]
	v_mfma_f32_16x16x32_bf16 v[6:9], v[160:163], v[216:219], v[6:9]
	v_mfma_f32_16x16x32_bf16 v[2:5], v[168:171], v[216:219], v[2:5]
	v_mfma_f32_16x16x32_bf16 v[54:57], v[164:167], v[180:183], v[54:57]
	v_mfma_f32_16x16x32_bf16 v[50:53], v[172:175], v[180:183], v[50:53]
	v_mfma_f32_16x16x32_bf16 v[38:41], v[164:167], v[188:191], v[38:41]
	v_mfma_f32_16x16x32_bf16 v[34:37], v[172:175], v[188:191], v[34:37]
	v_mfma_f32_16x16x32_bf16 v[22:25], v[164:167], v[212:215], v[22:25]
	v_mfma_f32_16x16x32_bf16 v[18:21], v[172:175], v[212:215], v[18:21]
	v_mfma_f32_16x16x32_bf16 v[6:9], v[164:167], v[220:223], v[6:9]
	v_mfma_f32_16x16x32_bf16 v[2:5], v[172:175], v[220:223], v[2:5]
	s_waitcnt vmcnt(8)
	s_barrier
	s_add_i32 s73, s73, 2
	s_add_u32 s72, s72, 0x100
	s_addc_u32 s63, s63, 0
	s_add_u32 s24, s24, 0x100
	s_addc_u32 s25, s25, 0
	s_cmp_gt_u32 s73, 29
	s_cbranch_scc0 .LBB0_1153
	s_branch .Lup2_exit
; #define PG8_STAGE(bufoff, gbase, voff) do { _Pragma("unroll") for (int _i = 0; _i < 2; ++_i) \
;         __builtin_amdgcn_global_load_lds((const unsigned*)((const char*)(gbase) + (voff)[_i]), (PG8_LAS unsigned*)(lds + (bufoff) + ldsw + _i * 8192), 16, 0, 0); } while (0)
; #define PG8_LDA(dst, b, h) do { _Pragma("unroll") for (int m = 0; m < 4; ++m) _Pragma("unroll") for (int k = 0; k < 2; ++k) dst[m][k] = *(const PG8_LAS bf16x8*)(lds + PG8_SA(b, h) + aoff + m * 2048 + k * 1024); } while (0)
; #define PG8_LDB(dst, b, h) do { _Pragma("unroll") for (int n = 0; n < 2; ++n) _Pragma("unroll") for (int k = 0; k < 2; ++k) dst[n][k] = *(const PG8_LAS bf16x8*)(lds + PG8_SB(b, h) + boff + n * 2048 + k * 1024); } while (0)
; #define PG8_MMA(ai, bj, At, Bt) do { __builtin_amdgcn_s_setprio(1); _Pragma("unroll") for (int m = 0; m < 4; ++m) _Pragma("unroll") for (int n = 0; n < 2; ++n) _Pragma("unroll") for (int k = 0; k < 2; ++k) \
;         acc[ai][bj][m][n] = __builtin_amdgcn_mfma_f32_16x16x32_bf16(Bt[n][k], At[m][k], acc[ai][bj][m][n], 0, 0, 0); __builtin_amdgcn_s_setprio(0); } while (0)
; #define PG8_WAIT_V(n) asm volatile("s_waitcnt vmcnt(" #n ")" ::: "memory")
; #define PG8_WAIT_L(n) asm volatile("s_waitcnt lgkmcnt(" #n ")" ::: "memory")
; #define PG8_BAR __builtin_amdgcn_s_barrier()
; #define PG8_SCHED __builtin_amdgcn_sched_barrier(0)
; template <class Epi, class Sched, bool ALIGN_EPI = false, bool SP2 = false>
; __device__ __forceinline__ void gemm_phase(PG8_LAS unsigned char* lds, const Gemm g, const Sched& S, const Epi& E, int wid_in) {
;     ...
;             PG8_LDB(B0, 0, 0); PG8_LDB(B1, 0, 1); PG8_SCHED; PG8_LDA(At, 0, 0); PG8_STAGE(PG8_SA(1, 1), a1 + hstep, voffA);
;             PG8_WAIT_V(8); PG8_WAIT_L(0); PG8_BAR; PG8_MMA(0, 0, At, B0); PG8_MMA(0, 1, At, B1); PG8_BAR; PG8_SCHED;
;             PG8_LDA(At, 0, 1); PG8_STAGE(PG8_SB(0, 0), b2, voffB); PG8_STAGE(PG8_SB(0, 1), b2 + hstep, voffB); PG8_STAGE(PG8_SA(0, 0), a2, voffA);
;             PG8_WAIT_V(8); PG8_WAIT_L(0); PG8_BAR; PG8_MMA(1, 0, At, B0); PG8_MMA(1, 1, At, B1); PG8_BAR; PG8_SCHED;
.Lup2_B:
	ds_read_b128 v[144:147], v224 offset:0
	ds_read_b128 v[148:151], v224 offset:1024
	ds_read_b128 v[152:155], v224 offset:2048
	ds_read_b128 v[156:159], v224 offset:3072
	ds_read_b128 v[160:163], v224 offset:16384
	ds_read_b128 v[164:167], v224 offset:17408
	ds_read_b128 v[168:171], v224 offset:18432
	ds_read_b128 v[172:175], v224 offset:19456
	ds_read_b128 v[176:179], v143 offset:0
	ds_read_b128 v[180:183], v143 offset:1024
	ds_read_b128 v[184:187], v143 offset:2048
	ds_read_b128 v[188:191], v143 offset:3072
	ds_read_b128 v[208:211], v143 offset:4096
	ds_read_b128 v[212:215], v143 offset:5120
	ds_read_b128 v[216:219], v143 offset:6144
	ds_read_b128 v[220:223], v143 offset:7168
	s_waitcnt vmcnt(8)
	s_waitcnt lgkmcnt(0)
	s_barrier
	v_mfma_f32_16x16x32_bf16 v[126:129], v[144:147], v[176:179], v[126:129]
	s_add_i32 m0, s59, 0x10000
	v_mfma_f32_16x16x32_bf16 v[122:125], v[152:155], v[176:179], v[122:125]
	global_load_lds_dwordx4 v0, s[26:27]
	v_mfma_f32_16x16x32_bf16 v[110:113], v[144:147], v[184:187], v[110:113]
	s_add_i32 m0, s59, 0x12000
	v_mfma_f32_16x16x32_bf16 v[106:109], v[152:155], v[184:187], v[106:109]
	global_load_lds_dwordx4 v130, s[26:27]
	v_mfma_f32_16x16x32_bf16 v[94:97], v[144:147], v[208:211], v[94:97]
	s_add_i32 m0, s59, 0x14000
	v_mfma_f32_16x16x32_bf16 v[90:93], v[152:155], v[208:211], v[90:93]
	global_load_lds_dwordx4 v0, s[40:41]
	v_mfma_f32_16x16x32_bf16 v[78:81], v[144:147], v[216:219], v[78:81]
	s_add_i32 m0, s59, 0x16000
	v_mfma_f32_16x16x32_bf16 v[74:77], v[152:155], v[216:219], v[74:77]
	global_load_lds_dwordx4 v130, s[40:41]
	v_mfma_f32_16x16x32_bf16 v[126:129], v[148:151], v[180:183], v[126:129]
	s_mov_b32 m0, s34
	v_mfma_f32_16x16x32_bf16 v[122:125], v[156:159], v[180:183], v[122:125]
	global_load_lds_dwordx4 v134, s[28:29]
	v_mfma_f32_16x16x32_bf16 v[110:113], v[148:151], v[188:191], v[110:113]
	s_mov_b32 m0, s35
	v_mfma_f32_16x16x32_bf16 v[106:109], v[156:159], v[188:191], v[106:109]
	global_load_lds_dwordx4 v132, s[28:29]
	v_mfma_f32_16x16x32_bf16 v[94:97], v[148:151], v[212:215], v[94:97]
	v_mfma_f32_16x16x32_bf16 v[90:93], v[156:159], v[212:215], v[90:93]
	v_mfma_f32_16x16x32_bf16 v[78:81], v[148:151], v[220:223], v[78:81]
	v_mfma_f32_16x16x32_bf16 v[74:77], v[156:159], v[220:223], v[74:77]
	v_mfma_f32_16x16x32_bf16 v[118:121], v[160:163], v[176:179], v[118:121]
	v_mfma_f32_16x16x32_bf16 v[114:117], v[168:171], v[176:179], v[114:117]
	v_mfma_f32_16x16x32_bf16 v[102:105], v[160:163], v[184:187], v[102:105]
	v_mfma_f32_16x16x32_bf16 v[98:101], v[168:171], v[184:187], v[98:101]
	v_mfma_f32_16x16x32_bf16 v[86:89], v[160:163], v[208:211], v[86:89]
	v_mfma_f32_16x16x32_bf16 v[82:85], v[168:171], v[208:211], v[82:85]
	v_mfma_f32_16x16x32_bf16 v[70:73], v[160:163], v[216:219], v[70:73]
	v_mfma_f32_16x16x32_bf16 v[66:69], v[168:171], v[216:219], v[66:69]
	v_mfma_f32_16x16x32_bf16 v[118:121], v[164:167], v[180:183], v[118:121]
	v_mfma_f32_16x16x32_bf16 v[114:117], v[172:175], v[180:183], v[114:117]
	v_mfma_f32_16x16x32_bf16 v[102:105], v[164:167], v[188:191], v[102:105]
	v_mfma_f32_16x16x32_bf16 v[98:101], v[172:175], v[188:191], v[98:101]
	v_mfma_f32_16x16x32_bf16 v[86:89], v[164:167], v[212:215], v[86:89]
	v_mfma_f32_16x16x32_bf16 v[82:85], v[172:175], v[212:215], v[82:85]
	v_mfma_f32_16x16x32_bf16 v[70:73], v[164:167], v[220:223], v[70:73]
	v_mfma_f32_16x16x32_bf16 v[66:69], v[172:175], v[220:223], v[66:69]
	s_barrier
	ds_read_b128 v[176:179], v143 offset:16384
	ds_read_b128 v[180:183], v143 offset:17408
	ds_read_b128 v[184:187], v143 offset:18432
	ds_read_b128 v[188:191], v143 offset:19456
	ds_read_b128 v[208:211], v143 offset:20480
	ds_read_b128 v[212:215], v143 offset:21504
	ds_read_b128 v[216:219], v143 offset:22528
	ds_read_b128 v[220:223], v143 offset:23552
	s_waitcnt vmcnt(8)
	s_waitcnt lgkmcnt(0)
	s_barrier
	v_mfma_f32_16x16x32_bf16 v[62:65], v[144:147], v[176:179], v[62:65]
	s_add_u32 s28, s28, 0x80000
	v_mfma_f32_16x16x32_bf16 v[58:61], v[152:155], v[176:179], v[58:61]
	s_addc_u32 s29, s29, 0
	v_mfma_f32_16x16x32_bf16 v[46:49], v[144:147], v[184:187], v[46:49]
	s_mov_b32 m0, s36
	v_mfma_f32_16x16x32_bf16 v[42:45], v[152:155], v[184:187], v[42:45]
	global_load_lds_dwordx4 v134, s[28:29]
	v_mfma_f32_16x16x32_bf16 v[30:33], v[144:147], v[208:211], v[30:33]
	s_mov_b32 m0, s37
	v_mfma_f32_16x16x32_bf16 v[26:29], v[152:155], v[208:211], v[26:29]
	global_load_lds_dwordx4 v132, s[28:29]
	v_mfma_f32_16x16x32_bf16 v[14:17], v[144:147], v[216:219], v[14:17]
	v_mfma_f32_16x16x32_bf16 v[10:13], v[152:155], v[216:219], v[10:13]
	v_mfma_f32_16x16x32_bf16 v[62:65], v[148:151], v[180:183], v[62:65]
	v_mfma_f32_16x16x32_bf16 v[58:61], v[156:159], v[180:183], v[58:61]
	v_mfma_f32_16x16x32_bf16 v[46:49], v[148:151], v[188:191], v[46:49]
	v_mfma_f32_16x16x32_bf16 v[42:45], v[156:159], v[188:191], v[42:45]
	v_mfma_f32_16x16x32_bf16 v[30:33], v[148:151], v[212:215], v[30:33]
	v_mfma_f32_16x16x32_bf16 v[26:29], v[156:159], v[212:215], v[26:29]
	v_mfma_f32_16x16x32_bf16 v[14:17], v[148:151], v[220:223], v[14:17]
	v_mfma_f32_16x16x32_bf16 v[10:13], v[156:159], v[220:223], v[10:13]
	v_mfma_f32_16x16x32_bf16 v[54:57], v[160:163], v[176:179], v[54:57]
	v_mfma_f32_16x16x32_bf16 v[50:53], v[168:171], v[176:179], v[50:53]
	v_mfma_f32_16x16x32_bf16 v[38:41], v[160:163], v[184:187], v[38:41]
	v_mfma_f32_16x16x32_bf16 v[34:37], v[168:171], v[184:187], v[34:37]
	v_mfma_f32_16x16x32_bf16 v[22:25], v[160:163], v[208:211], v[22:25]
	v_mfma_f32_16x16x32_bf16 v[18:21], v[168:171], v[208:211], v[18:21]
	v_mfma_f32_16x16x32_bf16 v[6:9], v[160:163], v[216:219], v[6:9]
	v_mfma_f32_16x16x32_bf16 v[2:5], v[168:171], v[216:219], v[2:5]
	v_mfma_f32_16x16x32_bf16 v[54:57], v[164:167], v[180:183], v[54:57]
	v_mfma_f32_16x16x32_bf16 v[50:53], v[172:175], v[180:183], v[50:53]
	v_mfma_f32_16x16x32_bf16 v[38:41], v[164:167], v[188:191], v[38:41]
	v_mfma_f32_16x16x32_bf16 v[34:37], v[172:175], v[188:191], v[34:37]
	v_mfma_f32_16x16x32_bf16 v[22:25], v[164:167], v[212:215], v[22:25]
	v_mfma_f32_16x16x32_bf16 v[18:21], v[172:175], v[212:215], v[18:21]
	v_mfma_f32_16x16x32_bf16 v[6:9], v[164:167], v[220:223], v[6:9]
	v_mfma_f32_16x16x32_bf16 v[2:5], v[172:175], v[220:223], v[2:5]
	s_barrier
; #define PG8_STAGE(bufoff, gbase, voff) do { _Pragma("unroll") for (int _i = 0; _i < 2; ++_i) \
;         __builtin_amdgcn_global_load_lds((const unsigned*)((const char*)(gbase) + (voff)[_i]), (PG8_LAS unsigned*)(lds + (bufoff) + ldsw + _i * 8192), 16, 0, 0); } while (0)
; #define PG8_LDA(dst, b, h) do { _Pragma("unroll") for (int m = 0; m < 4; ++m) _Pragma("unroll") for (int k = 0; k < 2; ++k) dst[m][k] = *(const PG8_LAS bf16x8*)(lds + PG8_SA(b, h) + aoff + m * 2048 + k * 1024); } while (0)
; #define PG8_LDB(dst, b, h) do { _Pragma("unroll") for (int n = 0; n < 2; ++n) _Pragma("unroll") for (int k = 0; k < 2; ++k) dst[n][k] = *(const PG8_LAS bf16x8*)(lds + PG8_SB(b, h) + boff + n * 2048 + k * 1024); } while (0)
; #define PG8_MMA(ai, bj, At, Bt) do { __builtin_amdgcn_s_setprio(1); _Pragma("unroll") for (int m = 0; m < 4; ++m) _Pragma("unroll") for (int n = 0; n < 2; ++n) _Pragma("unroll") for (int k = 0; k < 2; ++k) \
;         acc[ai][bj][m][n] = __builtin_amdgcn_mfma_f32_16x16x32_bf16(Bt[n][k], At[m][k], acc[ai][bj][m][n], 0, 0, 0); __builtin_amdgcn_s_setprio(0); } while (0)
; #define PG8_WAIT_V(n) asm volatile("s_waitcnt vmcnt(" #n ")" ::: "memory")
; #define PG8_WAIT_L(n) asm volatile("s_waitcnt lgkmcnt(" #n ")" ::: "memory")
; #define PG8_BAR __builtin_amdgcn_s_barrier()
; #define PG8_SCHED __builtin_amdgcn_sched_barrier(0)
; template <class Epi, class Sched, bool ALIGN_EPI = false, bool SP2 = false>
; __device__ __forceinline__ void gemm_phase(PG8_LAS unsigned char* lds, const Gemm g, const Sched& S, const Epi& E, int wid_in) {
;     ...
;             PG8_LDB(B0, 1, 0); PG8_LDB(B1, 1, 1); PG8_SCHED; PG8_LDA(At, 1, 0); PG8_STAGE(PG8_SA(0, 1), a2 + hstep, voffA);
;             PG8_WAIT_V(8); PG8_WAIT_L(0); PG8_BAR; PG8_MMA(0, 0, At, B0); PG8_MMA(0, 1, At, B1); PG8_BAR; PG8_SCHED;
;             PG8_LDA(At, 1, 1); PG8_STAGE(PG8_SB(1, 0), b3, voffB); PG8_STAGE(PG8_SB(1, 1), b3 + hstep, voffB); PG8_STAGE(PG8_SA(1, 0), a3, voffA);
;             PG8_WAIT_V(8); PG8_WAIT_L(0); PG8_BAR; PG8_MMA(1, 0, At, B0); PG8_MMA(1, 1, At, B1); PG8_BAR; PG8_SCHED;
	ds_read_b128 v[144:147], v224 offset:32768
	ds_read_b128 v[148:151], v224 offset:33792
	ds_read_b128 v[152:155], v224 offset:34816
	ds_read_b128 v[156:159], v224 offset:35840
	ds_read_b128 v[160:163], v224 offset:49152
	ds_read_b128 v[164:167], v224 offset:50176
	ds_read_b128 v[168:171], v224 offset:51200
	ds_read_b128 v[172:175], v224 offset:52224
	ds_read_b128 v[176:179], v143 offset:32768
	ds_read_b128 v[180:183], v143 offset:33792
	ds_read_b128 v[184:187], v143 offset:34816
	ds_read_b128 v[188:191], v143 offset:35840
	ds_read_b128 v[208:211], v143 offset:36864
	ds_read_b128 v[212:215], v143 offset:37888
	ds_read_b128 v[216:219], v143 offset:38912
	ds_read_b128 v[220:223], v143 offset:39936
	s_waitcnt vmcnt(8)
	s_waitcnt lgkmcnt(0)
	s_barrier
	v_mfma_f32_16x16x32_bf16 v[126:129], v[144:147], v[176:179], v[126:129]
	s_add_i32 m0, s59, 0x18000
	v_mfma_f32_16x16x32_bf16 v[122:125], v[152:155], v[176:179], v[122:125]
	global_load_lds_dwordx4 v0, s[98:99]
	v_mfma_f32_16x16x32_bf16 v[110:113], v[144:147], v[184:187], v[110:113]
	s_add_i32 m0, s59, 0x1a000
	v_mfma_f32_16x16x32_bf16 v[106:109], v[152:155], v[184:187], v[106:109]
	global_load_lds_dwordx4 v130, s[98:99]
	v_mfma_f32_16x16x32_bf16 v[94:97], v[144:147], v[208:211], v[94:97]
	s_add_u32 s26, s26, 0x80080
	v_mfma_f32_16x16x32_bf16 v[90:93], v[152:155], v[208:211], v[90:93]
	s_addc_u32 s27, s27, 0
	v_mfma_f32_16x16x32_bf16 v[78:81], v[144:147], v[216:219], v[78:81]
	s_add_i32 m0, s59, 0x1c000
	v_mfma_f32_16x16x32_bf16 v[74:77], v[152:155], v[216:219], v[74:77]
	global_load_lds_dwordx4 v0, s[26:27]
	v_mfma_f32_16x16x32_bf16 v[126:129], v[148:151], v[180:183], v[126:129]
	s_add_i32 m0, s59, 0x1e000
	v_mfma_f32_16x16x32_bf16 v[122:125], v[156:159], v[180:183], v[122:125]
	global_load_lds_dwordx4 v130, s[26:27]
	v_mfma_f32_16x16x32_bf16 v[110:113], v[148:151], v[188:191], v[110:113]
	s_mov_b32 m0, s48
	v_mfma_f32_16x16x32_bf16 v[106:109], v[156:159], v[188:191], v[106:109]
	global_load_lds_dwordx4 v134, s[100:101]
	v_mfma_f32_16x16x32_bf16 v[94:97], v[148:151], v[212:215], v[94:97]
	s_mov_b32 m0, s52
	v_mfma_f32_16x16x32_bf16 v[90:93], v[156:159], v[212:215], v[90:93]
	global_load_lds_dwordx4 v132, s[100:101]
	v_mfma_f32_16x16x32_bf16 v[78:81], v[148:151], v[220:223], v[78:81]
	v_mfma_f32_16x16x32_bf16 v[74:77], v[156:159], v[220:223], v[74:77]
	v_mfma_f32_16x16x32_bf16 v[118:121], v[160:163], v[176:179], v[118:121]
	v_mfma_f32_16x16x32_bf16 v[114:117], v[168:171], v[176:179], v[114:117]
	v_mfma_f32_16x16x32_bf16 v[102:105], v[160:163], v[184:187], v[102:105]
	v_mfma_f32_16x16x32_bf16 v[98:101], v[168:171], v[184:187], v[98:101]
	v_mfma_f32_16x16x32_bf16 v[86:89], v[160:163], v[208:211], v[86:89]
	v_mfma_f32_16x16x32_bf16 v[82:85], v[168:171], v[208:211], v[82:85]
	v_mfma_f32_16x16x32_bf16 v[70:73], v[160:163], v[216:219], v[70:73]
	v_mfma_f32_16x16x32_bf16 v[66:69], v[168:171], v[216:219], v[66:69]
	v_mfma_f32_16x16x32_bf16 v[118:121], v[164:167], v[180:183], v[118:121]
	v_mfma_f32_16x16x32_bf16 v[114:117], v[172:175], v[180:183], v[114:117]
	v_mfma_f32_16x16x32_bf16 v[102:105], v[164:167], v[188:191], v[102:105]
	v_mfma_f32_16x16x32_bf16 v[98:101], v[172:175], v[188:191], v[98:101]
	v_mfma_f32_16x16x32_bf16 v[86:89], v[164:167], v[212:215], v[86:89]
	v_mfma_f32_16x16x32_bf16 v[82:85], v[172:175], v[212:215], v[82:85]
	v_mfma_f32_16x16x32_bf16 v[70:73], v[164:167], v[220:223], v[70:73]
	v_mfma_f32_16x16x32_bf16 v[66:69], v[172:175], v[220:223], v[66:69]
	s_barrier
	ds_read_b128 v[176:179], v143 offset:49152
	ds_read_b128 v[180:183], v143 offset:50176
	ds_read_b128 v[184:187], v143 offset:51200
	ds_read_b128 v[188:191], v143 offset:52224
	ds_read_b128 v[208:211], v143 offset:53248
	ds_read_b128 v[212:215], v143 offset:54272
	ds_read_b128 v[216:219], v143 offset:55296
	ds_read_b128 v[220:223], v143 offset:56320
	s_waitcnt vmcnt(8)
	s_waitcnt lgkmcnt(0)
	s_barrier
	v_mfma_f32_16x16x32_bf16 v[62:65], v[144:147], v[176:179], v[62:65]
	s_add_u32 s98, s100, 0x80000
	v_mfma_f32_16x16x32_bf16 v[58:61], v[152:155], v[176:179], v[58:61]
	s_addc_u32 s99, s101, 0
	v_mfma_f32_16x16x32_bf16 v[46:49], v[144:147], v[184:187], v[46:49]
	s_add_i32 m0, s34, 0xc000
	v_mfma_f32_16x16x32_bf16 v[42:45], v[152:155], v[184:187], v[42:45]
	global_load_lds_dwordx4 v138, s[98:99]
	v_mfma_f32_16x16x32_bf16 v[30:33], v[144:147], v[208:211], v[30:33]
	s_add_i32 m0, s34, 0xe000
	v_mfma_f32_16x16x32_bf16 v[26:29], v[152:155], v[208:211], v[26:29]
	global_load_lds_dwordx4 v136, s[98:99]
	v_mfma_f32_16x16x32_bf16 v[14:17], v[144:147], v[216:219], v[14:17]
	v_mfma_f32_16x16x32_bf16 v[10:13], v[152:155], v[216:219], v[10:13]
	v_mfma_f32_16x16x32_bf16 v[62:65], v[148:151], v[180:183], v[62:65]
	v_mfma_f32_16x16x32_bf16 v[58:61], v[156:159], v[180:183], v[58:61]
	v_mfma_f32_16x16x32_bf16 v[46:49], v[148:151], v[188:191], v[46:49]
	v_mfma_f32_16x16x32_bf16 v[42:45], v[156:159], v[188:191], v[42:45]
	v_mfma_f32_16x16x32_bf16 v[30:33], v[148:151], v[212:215], v[30:33]
	v_mfma_f32_16x16x32_bf16 v[26:29], v[156:159], v[212:215], v[26:29]
	v_mfma_f32_16x16x32_bf16 v[14:17], v[148:151], v[220:223], v[14:17]
	v_mfma_f32_16x16x32_bf16 v[10:13], v[156:159], v[220:223], v[10:13]
	v_mfma_f32_16x16x32_bf16 v[54:57], v[160:163], v[176:179], v[54:57]
	v_mfma_f32_16x16x32_bf16 v[50:53], v[168:171], v[176:179], v[50:53]
	v_mfma_f32_16x16x32_bf16 v[38:41], v[160:163], v[184:187], v[38:41]
	v_mfma_f32_16x16x32_bf16 v[34:37], v[168:171], v[184:187], v[34:37]
	v_mfma_f32_16x16x32_bf16 v[22:25], v[160:163], v[208:211], v[22:25]
	v_mfma_f32_16x16x32_bf16 v[18:21], v[168:171], v[208:211], v[18:21]
	v_mfma_f32_16x16x32_bf16 v[6:9], v[160:163], v[216:219], v[6:9]
	v_mfma_f32_16x16x32_bf16 v[2:5], v[168:171], v[216:219], v[2:5]
	v_mfma_f32_16x16x32_bf16 v[54:57], v[164:167], v[180:183], v[54:57]
	v_mfma_f32_16x16x32_bf16 v[50:53], v[172:175], v[180:183], v[50:53]
	v_mfma_f32_16x16x32_bf16 v[38:41], v[164:167], v[188:191], v[38:41]
	v_mfma_f32_16x16x32_bf16 v[34:37], v[172:175], v[188:191], v[34:37]
	v_mfma_f32_16x16x32_bf16 v[22:25], v[164:167], v[212:215], v[22:25]
	v_mfma_f32_16x16x32_bf16 v[18:21], v[172:175], v[212:215], v[18:21]
	v_mfma_f32_16x16x32_bf16 v[6:9], v[164:167], v[220:223], v[6:9]
	v_mfma_f32_16x16x32_bf16 v[2:5], v[172:175], v[220:223], v[2:5]
	s_barrier
	s_add_i32 s73, s73, 2
	s_add_u32 s72, s72, 0x100
	s_addc_u32 s63, s63, 0
	s_add_u32 s24, s24, 0x100
	s_addc_u32 s25, s25, 0
	s_cmp_gt_u32 s73, 29
	s_cbranch_scc0 .LBB0_1153
.Lup2_exit:
	s_setprio 0
	s_and_b64 vcc, exec, s[14:15]
	s_cbranch_vccz .LBB0_1156
	s_barrier
